# attention waits + lag DMA + scan block v5 (LDS prefetch reads moved out of the DPP gaps)
# speedup vs baseline: 1.0071x; 1.0064x over previous
.LBB0_1010:
	s_mov_b64 s[78:79], -1
	s_and_b64 vcc, exec, s[70:71]
	s_cbranch_vccz .LBB0_1014
	s_setprio 1
	s_and_b32 s55, s53, 1
	s_lshl_b32 s56, s55, 14
	s_mul_i32 s55, s55, 0xaa00
	v_or_b32_e32 v99, s56, v143
	v_lshl_add_u32 v96, v106, 2, s55
	v_lshl_add_u32 v97, v101, 2, s55
	v_mov_b32_e32 v98, s55
	v_add_u32_e32 v99, 0x15400, v99
	s_waitcnt vmcnt(0)
	ds_read_b128 v[170:173], v96 offset:256
	ds_read_b128 v[174:177], v96 offset:512
	ds_read_b128 v[166:169], v96
	ds_read_b128 v[182:185], v96 offset:1024
	ds_read_b128 v[178:181], v96 offset:768
	ds_read_b32 v186, v97 offset:1280
	ds_read_b64 v[188:189], v98 offset:1344
	ds_read_b128 v[194:197], v96 offset:1616
	ds_read_b128 v[198:201], v96 offset:1872
	ds_read_b128 v[190:193], v96 offset:1360
	ds_read_b128 v[206:209], v96 offset:2384
	ds_read_b128 v[202:205], v96 offset:2128
	ds_read_b32 v210, v97 offset:2640
	ds_read_b64 v[220:221], v98 offset:2704
	v_mov_b64_e32 v[48:49], v[92:93]
	v_mov_b64_e32 v[52:53], v[94:95]
	s_waitcnt lgkmcnt(7)
	v_pk_mul_f32 v[58:59], v[52:53], v[170:171] op_sel_hi:[0,1]
	ds_read_b128 v[32:35], v96 offset:2976
	ds_read_b128 v[36:39], v96 offset:3232
	v_pk_fma_f32 v[58:59], v[52:53], v[172:173], v[58:59] op_sel:[1,0,0]
	ds_read_b128 v[28:31], v96 offset:2720
	ds_read_b128 v[44:47], v96 offset:3744
	v_pk_fma_f32 v[58:59], v[48:49], v[174:175], v[58:59] op_sel_hi:[0,1,1]
	ds_read_b128 v[40:43], v96 offset:3488
	v_pk_fma_f32 v[58:59], v[48:49], v[176:177], v[58:59] op_sel:[1,0,0]
	v_pk_mul_f32 v[64:65], v[186:187], v[182:183] op_sel_hi:[0,1]
	v_pk_mul_f32 v[66:67], v[186:187], v[184:185] op_sel_hi:[0,1]
	v_add_f32_dpp v58, v58, v58 row_ror:8 row_mask:0xf bank_mask:0xf bound_ctrl:1
	v_pk_fma_f32 v[64:65], v[52:53], v[166:167], v[64:65]
	v_pk_fma_f32 v[66:67], v[48:49], v[168:169], v[66:67]
	v_add_f32_dpp v58, v58, v58 row_ror:4 row_mask:0xf bank_mask:0xf bound_ctrl:1
	v_add_f32_dpp v60, v59, v59 row_ror:8 row_mask:0xf bank_mask:0xf bound_ctrl:1
	s_nop 0
	v_add_f32_dpp v58, v58, v58 row_ror:2 row_mask:0xf bank_mask:0xf bound_ctrl:1
	v_fma_f32 v61, v186, v189, v60
	s_nop 0
	v_add_f32_dpp v58, v58, v58 row_ror:1 row_mask:0xf bank_mask:0xf bound_ctrl:1
	v_pk_fma_f32 v[52:53], v[58:59], v[178:179], v[64:65] op_sel_hi:[0,1,1]
	v_pk_fma_f32 v[48:49], v[58:59], v[180:181], v[66:67] op_sel_hi:[0,1,1]
	v_fma_f32 v61, v58, v188, v61
	ds_read_b32 v54, v97 offset:4000
	ds_read_b64 v[56:57], v98 offset:4064
	ds_write_b32 v99, v61
	s_waitcnt lgkmcnt(8)
	v_pk_mul_f32 v[58:59], v[52:53], v[194:195] op_sel_hi:[0,1]
	ds_read_b128 v[170:173], v96 offset:4336
	ds_read_b128 v[174:177], v96 offset:4592
	v_pk_fma_f32 v[58:59], v[52:53], v[196:197], v[58:59] op_sel:[1,0,0]
	ds_read_b128 v[166:169], v96 offset:4080
	ds_read_b128 v[182:185], v96 offset:5104
	v_pk_fma_f32 v[58:59], v[48:49], v[198:199], v[58:59] op_sel_hi:[0,1,1]
	ds_read_b128 v[178:181], v96 offset:4848
	v_pk_fma_f32 v[58:59], v[48:49], v[200:201], v[58:59] op_sel:[1,0,0]
	v_pk_mul_f32 v[64:65], v[210:211], v[206:207] op_sel_hi:[0,1]
	v_pk_mul_f32 v[66:67], v[210:211], v[208:209] op_sel_hi:[0,1]
	v_add_f32_dpp v58, v58, v58 row_ror:8 row_mask:0xf bank_mask:0xf bound_ctrl:1
	v_pk_fma_f32 v[64:65], v[52:53], v[190:191], v[64:65]
	v_pk_fma_f32 v[66:67], v[48:49], v[192:193], v[66:67]
	v_add_f32_dpp v58, v58, v58 row_ror:4 row_mask:0xf bank_mask:0xf bound_ctrl:1
	v_add_f32_dpp v60, v59, v59 row_ror:8 row_mask:0xf bank_mask:0xf bound_ctrl:1
	s_nop 0
	v_add_f32_dpp v58, v58, v58 row_ror:2 row_mask:0xf bank_mask:0xf bound_ctrl:1
	v_fma_f32 v61, v210, v221, v60
	s_nop 0
	v_add_f32_dpp v58, v58, v58 row_ror:1 row_mask:0xf bank_mask:0xf bound_ctrl:1
	v_pk_fma_f32 v[52:53], v[58:59], v[202:203], v[64:65] op_sel_hi:[0,1,1]
	v_pk_fma_f32 v[48:49], v[58:59], v[204:205], v[66:67] op_sel_hi:[0,1,1]
	v_fma_f32 v61, v58, v220, v61
	ds_read_b32 v186, v97 offset:5360
	ds_read_b64 v[188:189], v98 offset:5424
	ds_write_b32 v99, v61 offset:512
	s_waitcnt lgkmcnt(9)
	v_pk_mul_f32 v[58:59], v[52:53], v[32:33] op_sel_hi:[0,1]
	ds_read_b128 v[194:197], v96 offset:5696
	ds_read_b128 v[198:201], v96 offset:5952
	v_pk_fma_f32 v[58:59], v[52:53], v[34:35], v[58:59] op_sel:[1,0,0]
	ds_read_b128 v[190:193], v96 offset:5440
	ds_read_b128 v[206:209], v96 offset:6464
	v_pk_fma_f32 v[58:59], v[48:49], v[36:37], v[58:59] op_sel_hi:[0,1,1]
	ds_read_b128 v[202:205], v96 offset:6208
	v_pk_fma_f32 v[58:59], v[48:49], v[38:39], v[58:59] op_sel:[1,0,0]
	v_pk_mul_f32 v[64:65], v[54:55], v[44:45] op_sel_hi:[0,1]
	v_pk_mul_f32 v[66:67], v[54:55], v[46:47] op_sel_hi:[0,1]
	v_add_f32_dpp v58, v58, v58 row_ror:8 row_mask:0xf bank_mask:0xf bound_ctrl:1
	v_pk_fma_f32 v[64:65], v[52:53], v[28:29], v[64:65]
	v_pk_fma_f32 v[66:67], v[48:49], v[30:31], v[66:67]
	v_add_f32_dpp v58, v58, v58 row_ror:4 row_mask:0xf bank_mask:0xf bound_ctrl:1
	v_add_f32_dpp v60, v59, v59 row_ror:8 row_mask:0xf bank_mask:0xf bound_ctrl:1
	s_nop 0
	v_add_f32_dpp v58, v58, v58 row_ror:2 row_mask:0xf bank_mask:0xf bound_ctrl:1
	v_fma_f32 v61, v54, v57, v60
	s_nop 0
	v_add_f32_dpp v58, v58, v58 row_ror:1 row_mask:0xf bank_mask:0xf bound_ctrl:1
	v_pk_fma_f32 v[52:53], v[58:59], v[40:41], v[64:65] op_sel_hi:[0,1,1]
	v_pk_fma_f32 v[48:49], v[58:59], v[42:43], v[66:67] op_sel_hi:[0,1,1]
	v_fma_f32 v61, v58, v56, v61
	ds_read_b32 v210, v97 offset:6720
	ds_read_b64 v[220:221], v98 offset:6784
	ds_write_b32 v99, v61 offset:1024
	s_waitcnt lgkmcnt(9)
	v_pk_mul_f32 v[58:59], v[52:53], v[170:171] op_sel_hi:[0,1]
	ds_read_b128 v[32:35], v96 offset:7056
	ds_read_b128 v[36:39], v96 offset:7312
	v_pk_fma_f32 v[58:59], v[52:53], v[172:173], v[58:59] op_sel:[1,0,0]
	ds_read_b128 v[28:31], v96 offset:6800
	ds_read_b128 v[44:47], v96 offset:7824
	v_pk_fma_f32 v[58:59], v[48:49], v[174:175], v[58:59] op_sel_hi:[0,1,1]
	ds_read_b128 v[40:43], v96 offset:7568
	v_pk_fma_f32 v[58:59], v[48:49], v[176:177], v[58:59] op_sel:[1,0,0]
	v_pk_mul_f32 v[64:65], v[186:187], v[182:183] op_sel_hi:[0,1]
	v_pk_mul_f32 v[66:67], v[186:187], v[184:185] op_sel_hi:[0,1]
	v_add_f32_dpp v58, v58, v58 row_ror:8 row_mask:0xf bank_mask:0xf bound_ctrl:1
	v_pk_fma_f32 v[64:65], v[52:53], v[166:167], v[64:65]
	v_pk_fma_f32 v[66:67], v[48:49], v[168:169], v[66:67]
	v_add_f32_dpp v58, v58, v58 row_ror:4 row_mask:0xf bank_mask:0xf bound_ctrl:1
	v_add_f32_dpp v60, v59, v59 row_ror:8 row_mask:0xf bank_mask:0xf bound_ctrl:1
	s_nop 0
	v_add_f32_dpp v58, v58, v58 row_ror:2 row_mask:0xf bank_mask:0xf bound_ctrl:1
	v_fma_f32 v61, v186, v189, v60
	s_nop 0
	v_add_f32_dpp v58, v58, v58 row_ror:1 row_mask:0xf bank_mask:0xf bound_ctrl:1
	v_pk_fma_f32 v[52:53], v[58:59], v[178:179], v[64:65] op_sel_hi:[0,1,1]
	v_pk_fma_f32 v[48:49], v[58:59], v[180:181], v[66:67] op_sel_hi:[0,1,1]
	v_fma_f32 v61, v58, v188, v61
	ds_read_b32 v54, v97 offset:8080
	ds_read_b64 v[56:57], v98 offset:8144
	ds_write_b32 v99, v61 offset:1536
	s_waitcnt lgkmcnt(9)
	v_pk_mul_f32 v[58:59], v[52:53], v[194:195] op_sel_hi:[0,1]
	ds_read_b128 v[170:173], v96 offset:8416
	ds_read_b128 v[174:177], v96 offset:8672
	v_pk_fma_f32 v[58:59], v[52:53], v[196:197], v[58:59] op_sel:[1,0,0]
	ds_read_b128 v[166:169], v96 offset:8160
	ds_read_b128 v[182:185], v96 offset:9184
	v_pk_fma_f32 v[58:59], v[48:49], v[198:199], v[58:59] op_sel_hi:[0,1,1]
	ds_read_b128 v[178:181], v96 offset:8928
	v_pk_fma_f32 v[58:59], v[48:49], v[200:201], v[58:59] op_sel:[1,0,0]
	v_pk_mul_f32 v[64:65], v[210:211], v[206:207] op_sel_hi:[0,1]
	v_pk_mul_f32 v[66:67], v[210:211], v[208:209] op_sel_hi:[0,1]
	v_add_f32_dpp v58, v58, v58 row_ror:8 row_mask:0xf bank_mask:0xf bound_ctrl:1
	v_pk_fma_f32 v[64:65], v[52:53], v[190:191], v[64:65]
	v_pk_fma_f32 v[66:67], v[48:49], v[192:193], v[66:67]
	v_add_f32_dpp v58, v58, v58 row_ror:4 row_mask:0xf bank_mask:0xf bound_ctrl:1
	v_add_f32_dpp v60, v59, v59 row_ror:8 row_mask:0xf bank_mask:0xf bound_ctrl:1
	s_nop 0
	v_add_f32_dpp v58, v58, v58 row_ror:2 row_mask:0xf bank_mask:0xf bound_ctrl:1
	v_fma_f32 v61, v210, v221, v60
	s_nop 0
	v_add_f32_dpp v58, v58, v58 row_ror:1 row_mask:0xf bank_mask:0xf bound_ctrl:1
	v_pk_fma_f32 v[52:53], v[58:59], v[202:203], v[64:65] op_sel_hi:[0,1,1]
	v_pk_fma_f32 v[48:49], v[58:59], v[204:205], v[66:67] op_sel_hi:[0,1,1]
	v_fma_f32 v61, v58, v220, v61
	ds_read_b32 v186, v97 offset:9440
	ds_read_b64 v[188:189], v98 offset:9504
	ds_write_b32 v99, v61 offset:2048
	s_waitcnt lgkmcnt(9)
	v_pk_mul_f32 v[58:59], v[52:53], v[32:33] op_sel_hi:[0,1]
	ds_read_b128 v[194:197], v96 offset:9776
	ds_read_b128 v[198:201], v96 offset:10032
	v_pk_fma_f32 v[58:59], v[52:53], v[34:35], v[58:59] op_sel:[1,0,0]
	ds_read_b128 v[190:193], v96 offset:9520
	ds_read_b128 v[206:209], v96 offset:10544
	v_pk_fma_f32 v[58:59], v[48:49], v[36:37], v[58:59] op_sel_hi:[0,1,1]
	ds_read_b128 v[202:205], v96 offset:10288
	v_pk_fma_f32 v[58:59], v[48:49], v[38:39], v[58:59] op_sel:[1,0,0]
	v_pk_mul_f32 v[64:65], v[54:55], v[44:45] op_sel_hi:[0,1]
	v_pk_mul_f32 v[66:67], v[54:55], v[46:47] op_sel_hi:[0,1]
	v_add_f32_dpp v58, v58, v58 row_ror:8 row_mask:0xf bank_mask:0xf bound_ctrl:1
	v_pk_fma_f32 v[64:65], v[52:53], v[28:29], v[64:65]
	v_pk_fma_f32 v[66:67], v[48:49], v[30:31], v[66:67]
	v_add_f32_dpp v58, v58, v58 row_ror:4 row_mask:0xf bank_mask:0xf bound_ctrl:1
	v_add_f32_dpp v60, v59, v59 row_ror:8 row_mask:0xf bank_mask:0xf bound_ctrl:1
	s_nop 0
	v_add_f32_dpp v58, v58, v58 row_ror:2 row_mask:0xf bank_mask:0xf bound_ctrl:1
	v_fma_f32 v61, v54, v57, v60
	s_nop 0
	v_add_f32_dpp v58, v58, v58 row_ror:1 row_mask:0xf bank_mask:0xf bound_ctrl:1
	v_pk_fma_f32 v[52:53], v[58:59], v[40:41], v[64:65] op_sel_hi:[0,1,1]
	v_pk_fma_f32 v[48:49], v[58:59], v[42:43], v[66:67] op_sel_hi:[0,1,1]
	v_fma_f32 v61, v58, v56, v61
	ds_read_b32 v210, v97 offset:10800
	ds_read_b64 v[220:221], v98 offset:10864
	ds_write_b32 v99, v61 offset:2560
	s_waitcnt lgkmcnt(9)
	v_pk_mul_f32 v[58:59], v[52:53], v[170:171] op_sel_hi:[0,1]
	ds_read_b128 v[32:35], v96 offset:11136
	ds_read_b128 v[36:39], v96 offset:11392
	v_pk_fma_f32 v[58:59], v[52:53], v[172:173], v[58:59] op_sel:[1,0,0]
	ds_read_b128 v[28:31], v96 offset:10880
	ds_read_b128 v[44:47], v96 offset:11904
	v_pk_fma_f32 v[58:59], v[48:49], v[174:175], v[58:59] op_sel_hi:[0,1,1]
	ds_read_b128 v[40:43], v96 offset:11648
	v_pk_fma_f32 v[58:59], v[48:49], v[176:177], v[58:59] op_sel:[1,0,0]
	v_pk_mul_f32 v[64:65], v[186:187], v[182:183] op_sel_hi:[0,1]
	v_pk_mul_f32 v[66:67], v[186:187], v[184:185] op_sel_hi:[0,1]
	v_add_f32_dpp v58, v58, v58 row_ror:8 row_mask:0xf bank_mask:0xf bound_ctrl:1
	v_pk_fma_f32 v[64:65], v[52:53], v[166:167], v[64:65]
	v_pk_fma_f32 v[66:67], v[48:49], v[168:169], v[66:67]
	v_add_f32_dpp v58, v58, v58 row_ror:4 row_mask:0xf bank_mask:0xf bound_ctrl:1
	v_add_f32_dpp v60, v59, v59 row_ror:8 row_mask:0xf bank_mask:0xf bound_ctrl:1
	s_nop 0
	v_add_f32_dpp v58, v58, v58 row_ror:2 row_mask:0xf bank_mask:0xf bound_ctrl:1
	v_fma_f32 v61, v186, v189, v60
	s_nop 0
	v_add_f32_dpp v58, v58, v58 row_ror:1 row_mask:0xf bank_mask:0xf bound_ctrl:1
	v_pk_fma_f32 v[52:53], v[58:59], v[178:179], v[64:65] op_sel_hi:[0,1,1]
	v_pk_fma_f32 v[48:49], v[58:59], v[180:181], v[66:67] op_sel_hi:[0,1,1]
	v_fma_f32 v61, v58, v188, v61
	ds_read_b32 v54, v97 offset:12160
	ds_read_b64 v[56:57], v98 offset:12224
	ds_write_b32 v99, v61 offset:3072
	s_waitcnt lgkmcnt(9)
	v_pk_mul_f32 v[58:59], v[52:53], v[194:195] op_sel_hi:[0,1]
	ds_read_b128 v[170:173], v96 offset:12496
	ds_read_b128 v[174:177], v96 offset:12752
	v_pk_fma_f32 v[58:59], v[52:53], v[196:197], v[58:59] op_sel:[1,0,0]
	ds_read_b128 v[166:169], v96 offset:12240
	ds_read_b128 v[182:185], v96 offset:13264
	v_pk_fma_f32 v[58:59], v[48:49], v[198:199], v[58:59] op_sel_hi:[0,1,1]
	ds_read_b128 v[178:181], v96 offset:13008
	v_pk_fma_f32 v[58:59], v[48:49], v[200:201], v[58:59] op_sel:[1,0,0]
	v_pk_mul_f32 v[64:65], v[210:211], v[206:207] op_sel_hi:[0,1]
	v_pk_mul_f32 v[66:67], v[210:211], v[208:209] op_sel_hi:[0,1]
	v_add_f32_dpp v58, v58, v58 row_ror:8 row_mask:0xf bank_mask:0xf bound_ctrl:1
	v_pk_fma_f32 v[64:65], v[52:53], v[190:191], v[64:65]
	v_pk_fma_f32 v[66:67], v[48:49], v[192:193], v[66:67]
	v_add_f32_dpp v58, v58, v58 row_ror:4 row_mask:0xf bank_mask:0xf bound_ctrl:1
	v_add_f32_dpp v60, v59, v59 row_ror:8 row_mask:0xf bank_mask:0xf bound_ctrl:1
	s_nop 0
	v_add_f32_dpp v58, v58, v58 row_ror:2 row_mask:0xf bank_mask:0xf bound_ctrl:1
	v_fma_f32 v61, v210, v221, v60
	s_nop 0
	v_add_f32_dpp v58, v58, v58 row_ror:1 row_mask:0xf bank_mask:0xf bound_ctrl:1
	v_pk_fma_f32 v[52:53], v[58:59], v[202:203], v[64:65] op_sel_hi:[0,1,1]
	v_pk_fma_f32 v[48:49], v[58:59], v[204:205], v[66:67] op_sel_hi:[0,1,1]
	v_fma_f32 v61, v58, v220, v61
	ds_read_b32 v186, v97 offset:13520
	ds_read_b64 v[188:189], v98 offset:13584
	ds_write_b32 v99, v61 offset:3584
	s_waitcnt lgkmcnt(9)
	v_pk_mul_f32 v[58:59], v[52:53], v[32:33] op_sel_hi:[0,1]
	ds_read_b128 v[194:197], v96 offset:13856
	ds_read_b128 v[198:201], v96 offset:14112
	v_pk_fma_f32 v[58:59], v[52:53], v[34:35], v[58:59] op_sel:[1,0,0]
	ds_read_b128 v[190:193], v96 offset:13600
	ds_read_b128 v[206:209], v96 offset:14624
	v_pk_fma_f32 v[58:59], v[48:49], v[36:37], v[58:59] op_sel_hi:[0,1,1]
	ds_read_b128 v[202:205], v96 offset:14368
	v_pk_fma_f32 v[58:59], v[48:49], v[38:39], v[58:59] op_sel:[1,0,0]
	v_pk_mul_f32 v[64:65], v[54:55], v[44:45] op_sel_hi:[0,1]
	v_pk_mul_f32 v[66:67], v[54:55], v[46:47] op_sel_hi:[0,1]
	v_add_f32_dpp v58, v58, v58 row_ror:8 row_mask:0xf bank_mask:0xf bound_ctrl:1
	v_pk_fma_f32 v[64:65], v[52:53], v[28:29], v[64:65]
	v_pk_fma_f32 v[66:67], v[48:49], v[30:31], v[66:67]
	v_add_f32_dpp v58, v58, v58 row_ror:4 row_mask:0xf bank_mask:0xf bound_ctrl:1
	v_add_f32_dpp v60, v59, v59 row_ror:8 row_mask:0xf bank_mask:0xf bound_ctrl:1
	s_nop 0
	v_add_f32_dpp v58, v58, v58 row_ror:2 row_mask:0xf bank_mask:0xf bound_ctrl:1
	v_fma_f32 v61, v54, v57, v60
	s_nop 0
	v_add_f32_dpp v58, v58, v58 row_ror:1 row_mask:0xf bank_mask:0xf bound_ctrl:1
	v_pk_fma_f32 v[52:53], v[58:59], v[40:41], v[64:65] op_sel_hi:[0,1,1]
	v_pk_fma_f32 v[48:49], v[58:59], v[42:43], v[66:67] op_sel_hi:[0,1,1]
	v_fma_f32 v61, v58, v56, v61
	ds_read_b32 v210, v97 offset:14880
	ds_read_b64 v[220:221], v98 offset:14944
	ds_write_b32 v99, v61 offset:4096
	s_waitcnt lgkmcnt(9)
	v_pk_mul_f32 v[58:59], v[52:53], v[170:171] op_sel_hi:[0,1]
	ds_read_b128 v[32:35], v96 offset:15216
	ds_read_b128 v[36:39], v96 offset:15472
	v_pk_fma_f32 v[58:59], v[52:53], v[172:173], v[58:59] op_sel:[1,0,0]
	ds_read_b128 v[28:31], v96 offset:14960
	ds_read_b128 v[44:47], v96 offset:15984
	v_pk_fma_f32 v[58:59], v[48:49], v[174:175], v[58:59] op_sel_hi:[0,1,1]
	ds_read_b128 v[40:43], v96 offset:15728
	v_pk_fma_f32 v[58:59], v[48:49], v[176:177], v[58:59] op_sel:[1,0,0]
	v_pk_mul_f32 v[64:65], v[186:187], v[182:183] op_sel_hi:[0,1]
	v_pk_mul_f32 v[66:67], v[186:187], v[184:185] op_sel_hi:[0,1]
	v_add_f32_dpp v58, v58, v58 row_ror:8 row_mask:0xf bank_mask:0xf bound_ctrl:1
	v_pk_fma_f32 v[64:65], v[52:53], v[166:167], v[64:65]
	v_pk_fma_f32 v[66:67], v[48:49], v[168:169], v[66:67]
	v_add_f32_dpp v58, v58, v58 row_ror:4 row_mask:0xf bank_mask:0xf bound_ctrl:1
	v_add_f32_dpp v60, v59, v59 row_ror:8 row_mask:0xf bank_mask:0xf bound_ctrl:1
	s_nop 0
	v_add_f32_dpp v58, v58, v58 row_ror:2 row_mask:0xf bank_mask:0xf bound_ctrl:1
	v_fma_f32 v61, v186, v189, v60
	s_nop 0
	v_add_f32_dpp v58, v58, v58 row_ror:1 row_mask:0xf bank_mask:0xf bound_ctrl:1
	v_pk_fma_f32 v[52:53], v[58:59], v[178:179], v[64:65] op_sel_hi:[0,1,1]
	v_pk_fma_f32 v[48:49], v[58:59], v[180:181], v[66:67] op_sel_hi:[0,1,1]
	v_fma_f32 v61, v58, v188, v61
	ds_read_b32 v54, v97 offset:16240
	ds_read_b64 v[56:57], v98 offset:16304
	ds_write_b32 v99, v61 offset:4608
	s_waitcnt lgkmcnt(9)
	v_pk_mul_f32 v[58:59], v[52:53], v[194:195] op_sel_hi:[0,1]
	ds_read_b128 v[170:173], v96 offset:16576
	ds_read_b128 v[174:177], v96 offset:16832
	v_pk_fma_f32 v[58:59], v[52:53], v[196:197], v[58:59] op_sel:[1,0,0]
	ds_read_b128 v[166:169], v96 offset:16320
	ds_read_b128 v[182:185], v96 offset:17344
	v_pk_fma_f32 v[58:59], v[48:49], v[198:199], v[58:59] op_sel_hi:[0,1,1]
	ds_read_b128 v[178:181], v96 offset:17088
	v_pk_fma_f32 v[58:59], v[48:49], v[200:201], v[58:59] op_sel:[1,0,0]
	v_pk_mul_f32 v[64:65], v[210:211], v[206:207] op_sel_hi:[0,1]
	v_pk_mul_f32 v[66:67], v[210:211], v[208:209] op_sel_hi:[0,1]
	v_add_f32_dpp v58, v58, v58 row_ror:8 row_mask:0xf bank_mask:0xf bound_ctrl:1
	v_pk_fma_f32 v[64:65], v[52:53], v[190:191], v[64:65]
	v_pk_fma_f32 v[66:67], v[48:49], v[192:193], v[66:67]
	v_add_f32_dpp v58, v58, v58 row_ror:4 row_mask:0xf bank_mask:0xf bound_ctrl:1
	v_add_f32_dpp v60, v59, v59 row_ror:8 row_mask:0xf bank_mask:0xf bound_ctrl:1
	s_nop 0
	v_add_f32_dpp v58, v58, v58 row_ror:2 row_mask:0xf bank_mask:0xf bound_ctrl:1
	v_fma_f32 v61, v210, v221, v60
	s_nop 0
	v_add_f32_dpp v58, v58, v58 row_ror:1 row_mask:0xf bank_mask:0xf bound_ctrl:1
	v_pk_fma_f32 v[52:53], v[58:59], v[202:203], v[64:65] op_sel_hi:[0,1,1]
	v_pk_fma_f32 v[48:49], v[58:59], v[204:205], v[66:67] op_sel_hi:[0,1,1]
	v_fma_f32 v61, v58, v220, v61
	ds_read_b32 v186, v97 offset:17600
	ds_read_b64 v[188:189], v98 offset:17664
	ds_write_b32 v99, v61 offset:5120
	s_waitcnt lgkmcnt(9)
	v_pk_mul_f32 v[58:59], v[52:53], v[32:33] op_sel_hi:[0,1]
	ds_read_b128 v[194:197], v96 offset:17936
	ds_read_b128 v[198:201], v96 offset:18192
	v_pk_fma_f32 v[58:59], v[52:53], v[34:35], v[58:59] op_sel:[1,0,0]
	ds_read_b128 v[190:193], v96 offset:17680
	ds_read_b128 v[206:209], v96 offset:18704
	v_pk_fma_f32 v[58:59], v[48:49], v[36:37], v[58:59] op_sel_hi:[0,1,1]
	ds_read_b128 v[202:205], v96 offset:18448
	v_pk_fma_f32 v[58:59], v[48:49], v[38:39], v[58:59] op_sel:[1,0,0]
	v_pk_mul_f32 v[64:65], v[54:55], v[44:45] op_sel_hi:[0,1]
	v_pk_mul_f32 v[66:67], v[54:55], v[46:47] op_sel_hi:[0,1]
	v_add_f32_dpp v58, v58, v58 row_ror:8 row_mask:0xf bank_mask:0xf bound_ctrl:1
	v_pk_fma_f32 v[64:65], v[52:53], v[28:29], v[64:65]
	v_pk_fma_f32 v[66:67], v[48:49], v[30:31], v[66:67]
	v_add_f32_dpp v58, v58, v58 row_ror:4 row_mask:0xf bank_mask:0xf bound_ctrl:1
	v_add_f32_dpp v60, v59, v59 row_ror:8 row_mask:0xf bank_mask:0xf bound_ctrl:1
	s_nop 0
	v_add_f32_dpp v58, v58, v58 row_ror:2 row_mask:0xf bank_mask:0xf bound_ctrl:1
	v_fma_f32 v61, v54, v57, v60
	s_nop 0
	v_add_f32_dpp v58, v58, v58 row_ror:1 row_mask:0xf bank_mask:0xf bound_ctrl:1
	v_pk_fma_f32 v[52:53], v[58:59], v[40:41], v[64:65] op_sel_hi:[0,1,1]
	v_pk_fma_f32 v[48:49], v[58:59], v[42:43], v[66:67] op_sel_hi:[0,1,1]
	v_fma_f32 v61, v58, v56, v61
	ds_read_b32 v210, v97 offset:18960
	ds_read_b64 v[220:221], v98 offset:19024
	ds_write_b32 v99, v61 offset:5632
	s_waitcnt lgkmcnt(9)
	v_pk_mul_f32 v[58:59], v[52:53], v[170:171] op_sel_hi:[0,1]
	ds_read_b128 v[32:35], v96 offset:19296
	ds_read_b128 v[36:39], v96 offset:19552
	v_pk_fma_f32 v[58:59], v[52:53], v[172:173], v[58:59] op_sel:[1,0,0]
	ds_read_b128 v[28:31], v96 offset:19040
	ds_read_b128 v[44:47], v96 offset:20064
	v_pk_fma_f32 v[58:59], v[48:49], v[174:175], v[58:59] op_sel_hi:[0,1,1]
	ds_read_b128 v[40:43], v96 offset:19808
	v_pk_fma_f32 v[58:59], v[48:49], v[176:177], v[58:59] op_sel:[1,0,0]
	v_pk_mul_f32 v[64:65], v[186:187], v[182:183] op_sel_hi:[0,1]
	v_pk_mul_f32 v[66:67], v[186:187], v[184:185] op_sel_hi:[0,1]
	v_add_f32_dpp v58, v58, v58 row_ror:8 row_mask:0xf bank_mask:0xf bound_ctrl:1
	v_pk_fma_f32 v[64:65], v[52:53], v[166:167], v[64:65]
	v_pk_fma_f32 v[66:67], v[48:49], v[168:169], v[66:67]
	v_add_f32_dpp v58, v58, v58 row_ror:4 row_mask:0xf bank_mask:0xf bound_ctrl:1
	v_add_f32_dpp v60, v59, v59 row_ror:8 row_mask:0xf bank_mask:0xf bound_ctrl:1
	s_nop 0
	v_add_f32_dpp v58, v58, v58 row_ror:2 row_mask:0xf bank_mask:0xf bound_ctrl:1
	v_fma_f32 v61, v186, v189, v60
	s_nop 0
	v_add_f32_dpp v58, v58, v58 row_ror:1 row_mask:0xf bank_mask:0xf bound_ctrl:1
	v_pk_fma_f32 v[52:53], v[58:59], v[178:179], v[64:65] op_sel_hi:[0,1,1]
	v_pk_fma_f32 v[48:49], v[58:59], v[180:181], v[66:67] op_sel_hi:[0,1,1]
	v_fma_f32 v61, v58, v188, v61
	ds_read_b32 v54, v97 offset:20320
	ds_read_b64 v[56:57], v98 offset:20384
	ds_write_b32 v99, v61 offset:6144
	s_waitcnt lgkmcnt(9)
	v_pk_mul_f32 v[58:59], v[52:53], v[194:195] op_sel_hi:[0,1]
	ds_read_b128 v[170:173], v96 offset:20656
	ds_read_b128 v[174:177], v96 offset:20912
	v_pk_fma_f32 v[58:59], v[52:53], v[196:197], v[58:59] op_sel:[1,0,0]
	ds_read_b128 v[166:169], v96 offset:20400
	ds_read_b128 v[182:185], v96 offset:21424
	v_pk_fma_f32 v[58:59], v[48:49], v[198:199], v[58:59] op_sel_hi:[0,1,1]
	ds_read_b128 v[178:181], v96 offset:21168
	v_pk_fma_f32 v[58:59], v[48:49], v[200:201], v[58:59] op_sel:[1,0,0]
	v_pk_mul_f32 v[64:65], v[210:211], v[206:207] op_sel_hi:[0,1]
	v_pk_mul_f32 v[66:67], v[210:211], v[208:209] op_sel_hi:[0,1]
	v_add_f32_dpp v58, v58, v58 row_ror:8 row_mask:0xf bank_mask:0xf bound_ctrl:1
	v_pk_fma_f32 v[64:65], v[52:53], v[190:191], v[64:65]
	v_pk_fma_f32 v[66:67], v[48:49], v[192:193], v[66:67]
	v_add_f32_dpp v58, v58, v58 row_ror:4 row_mask:0xf bank_mask:0xf bound_ctrl:1
	v_add_f32_dpp v60, v59, v59 row_ror:8 row_mask:0xf bank_mask:0xf bound_ctrl:1
	s_nop 0
	v_add_f32_dpp v58, v58, v58 row_ror:2 row_mask:0xf bank_mask:0xf bound_ctrl:1
	v_fma_f32 v61, v210, v221, v60
	s_nop 0
	v_add_f32_dpp v58, v58, v58 row_ror:1 row_mask:0xf bank_mask:0xf bound_ctrl:1
	v_pk_fma_f32 v[52:53], v[58:59], v[202:203], v[64:65] op_sel_hi:[0,1,1]
	v_pk_fma_f32 v[48:49], v[58:59], v[204:205], v[66:67] op_sel_hi:[0,1,1]
	v_fma_f32 v61, v58, v220, v61
	ds_read_b32 v186, v97 offset:21680
	ds_read_b64 v[188:189], v98 offset:21744
	ds_write_b32 v99, v61 offset:6656
	s_waitcnt lgkmcnt(9)
	v_pk_mul_f32 v[58:59], v[52:53], v[32:33] op_sel_hi:[0,1]
	ds_read_b128 v[194:197], v96 offset:22016
	ds_read_b128 v[198:201], v96 offset:22272
	v_pk_fma_f32 v[58:59], v[52:53], v[34:35], v[58:59] op_sel:[1,0,0]
	ds_read_b128 v[190:193], v96 offset:21760
	ds_read_b128 v[206:209], v96 offset:22784
	v_pk_fma_f32 v[58:59], v[48:49], v[36:37], v[58:59] op_sel_hi:[0,1,1]
	ds_read_b128 v[202:205], v96 offset:22528
	v_pk_fma_f32 v[58:59], v[48:49], v[38:39], v[58:59] op_sel:[1,0,0]
	v_pk_mul_f32 v[64:65], v[54:55], v[44:45] op_sel_hi:[0,1]
	v_pk_mul_f32 v[66:67], v[54:55], v[46:47] op_sel_hi:[0,1]
	v_add_f32_dpp v58, v58, v58 row_ror:8 row_mask:0xf bank_mask:0xf bound_ctrl:1
	v_pk_fma_f32 v[64:65], v[52:53], v[28:29], v[64:65]
	v_pk_fma_f32 v[66:67], v[48:49], v[30:31], v[66:67]
	v_add_f32_dpp v58, v58, v58 row_ror:4 row_mask:0xf bank_mask:0xf bound_ctrl:1
	v_add_f32_dpp v60, v59, v59 row_ror:8 row_mask:0xf bank_mask:0xf bound_ctrl:1
	s_nop 0
	v_add_f32_dpp v58, v58, v58 row_ror:2 row_mask:0xf bank_mask:0xf bound_ctrl:1
	v_fma_f32 v61, v54, v57, v60
	s_nop 0
	v_add_f32_dpp v58, v58, v58 row_ror:1 row_mask:0xf bank_mask:0xf bound_ctrl:1
	v_pk_fma_f32 v[52:53], v[58:59], v[40:41], v[64:65] op_sel_hi:[0,1,1]
	v_pk_fma_f32 v[48:49], v[58:59], v[42:43], v[66:67] op_sel_hi:[0,1,1]
	v_fma_f32 v61, v58, v56, v61
	ds_read_b32 v210, v97 offset:23040
	ds_read_b64 v[220:221], v98 offset:23104
	ds_write_b32 v99, v61 offset:7168
	s_waitcnt lgkmcnt(9)
	v_pk_mul_f32 v[58:59], v[52:53], v[170:171] op_sel_hi:[0,1]
	ds_read_b128 v[32:35], v96 offset:23376
	ds_read_b128 v[36:39], v96 offset:23632
	v_pk_fma_f32 v[58:59], v[52:53], v[172:173], v[58:59] op_sel:[1,0,0]
	ds_read_b128 v[28:31], v96 offset:23120
	ds_read_b128 v[44:47], v96 offset:24144
	v_pk_fma_f32 v[58:59], v[48:49], v[174:175], v[58:59] op_sel_hi:[0,1,1]
	ds_read_b128 v[40:43], v96 offset:23888
	v_pk_fma_f32 v[58:59], v[48:49], v[176:177], v[58:59] op_sel:[1,0,0]
	v_pk_mul_f32 v[64:65], v[186:187], v[182:183] op_sel_hi:[0,1]
	v_pk_mul_f32 v[66:67], v[186:187], v[184:185] op_sel_hi:[0,1]
	v_add_f32_dpp v58, v58, v58 row_ror:8 row_mask:0xf bank_mask:0xf bound_ctrl:1
	v_pk_fma_f32 v[64:65], v[52:53], v[166:167], v[64:65]
	v_pk_fma_f32 v[66:67], v[48:49], v[168:169], v[66:67]
	v_add_f32_dpp v58, v58, v58 row_ror:4 row_mask:0xf bank_mask:0xf bound_ctrl:1
	v_add_f32_dpp v60, v59, v59 row_ror:8 row_mask:0xf bank_mask:0xf bound_ctrl:1
	s_nop 0
	v_add_f32_dpp v58, v58, v58 row_ror:2 row_mask:0xf bank_mask:0xf bound_ctrl:1
	v_fma_f32 v61, v186, v189, v60
	s_nop 0
	v_add_f32_dpp v58, v58, v58 row_ror:1 row_mask:0xf bank_mask:0xf bound_ctrl:1
	v_pk_fma_f32 v[52:53], v[58:59], v[178:179], v[64:65] op_sel_hi:[0,1,1]
	v_pk_fma_f32 v[48:49], v[58:59], v[180:181], v[66:67] op_sel_hi:[0,1,1]
	v_fma_f32 v61, v58, v188, v61
	ds_read_b32 v54, v97 offset:24400
	ds_read_b64 v[56:57], v98 offset:24464
	ds_write_b32 v99, v61 offset:7680
	s_waitcnt lgkmcnt(9)
	v_pk_mul_f32 v[58:59], v[52:53], v[194:195] op_sel_hi:[0,1]
	ds_read_b128 v[170:173], v96 offset:24736
	ds_read_b128 v[174:177], v96 offset:24992
	v_pk_fma_f32 v[58:59], v[52:53], v[196:197], v[58:59] op_sel:[1,0,0]
	ds_read_b128 v[166:169], v96 offset:24480
	ds_read_b128 v[182:185], v96 offset:25504
	v_pk_fma_f32 v[58:59], v[48:49], v[198:199], v[58:59] op_sel_hi:[0,1,1]
	ds_read_b128 v[178:181], v96 offset:25248
	v_pk_fma_f32 v[58:59], v[48:49], v[200:201], v[58:59] op_sel:[1,0,0]
	v_pk_mul_f32 v[64:65], v[210:211], v[206:207] op_sel_hi:[0,1]
	v_pk_mul_f32 v[66:67], v[210:211], v[208:209] op_sel_hi:[0,1]
	v_add_f32_dpp v58, v58, v58 row_ror:8 row_mask:0xf bank_mask:0xf bound_ctrl:1
	v_pk_fma_f32 v[64:65], v[52:53], v[190:191], v[64:65]
	v_pk_fma_f32 v[66:67], v[48:49], v[192:193], v[66:67]
	v_add_f32_dpp v58, v58, v58 row_ror:4 row_mask:0xf bank_mask:0xf bound_ctrl:1
	v_add_f32_dpp v60, v59, v59 row_ror:8 row_mask:0xf bank_mask:0xf bound_ctrl:1
	s_nop 0
	v_add_f32_dpp v58, v58, v58 row_ror:2 row_mask:0xf bank_mask:0xf bound_ctrl:1
	v_fma_f32 v61, v210, v221, v60
	s_nop 0
	v_add_f32_dpp v58, v58, v58 row_ror:1 row_mask:0xf bank_mask:0xf bound_ctrl:1
	v_pk_fma_f32 v[52:53], v[58:59], v[202:203], v[64:65] op_sel_hi:[0,1,1]
	v_pk_fma_f32 v[48:49], v[58:59], v[204:205], v[66:67] op_sel_hi:[0,1,1]
	v_fma_f32 v61, v58, v220, v61
	ds_read_b32 v186, v97 offset:25760
	ds_read_b64 v[188:189], v98 offset:25824
	ds_write_b32 v99, v61 offset:8192
	s_waitcnt lgkmcnt(9)
	v_pk_mul_f32 v[58:59], v[52:53], v[32:33] op_sel_hi:[0,1]
	ds_read_b128 v[194:197], v96 offset:26096
	ds_read_b128 v[198:201], v96 offset:26352
	v_pk_fma_f32 v[58:59], v[52:53], v[34:35], v[58:59] op_sel:[1,0,0]
	ds_read_b128 v[190:193], v96 offset:25840
	ds_read_b128 v[206:209], v96 offset:26864
	v_pk_fma_f32 v[58:59], v[48:49], v[36:37], v[58:59] op_sel_hi:[0,1,1]
	ds_read_b128 v[202:205], v96 offset:26608
	v_pk_fma_f32 v[58:59], v[48:49], v[38:39], v[58:59] op_sel:[1,0,0]
	v_pk_mul_f32 v[64:65], v[54:55], v[44:45] op_sel_hi:[0,1]
	v_pk_mul_f32 v[66:67], v[54:55], v[46:47] op_sel_hi:[0,1]
	v_add_f32_dpp v58, v58, v58 row_ror:8 row_mask:0xf bank_mask:0xf bound_ctrl:1
	v_pk_fma_f32 v[64:65], v[52:53], v[28:29], v[64:65]
	v_pk_fma_f32 v[66:67], v[48:49], v[30:31], v[66:67]
	v_add_f32_dpp v58, v58, v58 row_ror:4 row_mask:0xf bank_mask:0xf bound_ctrl:1
	v_add_f32_dpp v60, v59, v59 row_ror:8 row_mask:0xf bank_mask:0xf bound_ctrl:1
	s_nop 0
	v_add_f32_dpp v58, v58, v58 row_ror:2 row_mask:0xf bank_mask:0xf bound_ctrl:1
	v_fma_f32 v61, v54, v57, v60
	s_nop 0
	v_add_f32_dpp v58, v58, v58 row_ror:1 row_mask:0xf bank_mask:0xf bound_ctrl:1
	v_pk_fma_f32 v[52:53], v[58:59], v[40:41], v[64:65] op_sel_hi:[0,1,1]
	v_pk_fma_f32 v[48:49], v[58:59], v[42:43], v[66:67] op_sel_hi:[0,1,1]
	v_fma_f32 v61, v58, v56, v61
	ds_read_b32 v210, v97 offset:27120
	ds_read_b64 v[220:221], v98 offset:27184
	ds_write_b32 v99, v61 offset:8704
	s_waitcnt lgkmcnt(9)
	v_pk_mul_f32 v[58:59], v[52:53], v[170:171] op_sel_hi:[0,1]
	ds_read_b128 v[32:35], v96 offset:27456
	ds_read_b128 v[36:39], v96 offset:27712
	v_pk_fma_f32 v[58:59], v[52:53], v[172:173], v[58:59] op_sel:[1,0,0]
	ds_read_b128 v[28:31], v96 offset:27200
	ds_read_b128 v[44:47], v96 offset:28224
	v_pk_fma_f32 v[58:59], v[48:49], v[174:175], v[58:59] op_sel_hi:[0,1,1]
	ds_read_b128 v[40:43], v96 offset:27968
	v_pk_fma_f32 v[58:59], v[48:49], v[176:177], v[58:59] op_sel:[1,0,0]
	v_pk_mul_f32 v[64:65], v[186:187], v[182:183] op_sel_hi:[0,1]
	v_pk_mul_f32 v[66:67], v[186:187], v[184:185] op_sel_hi:[0,1]
	v_add_f32_dpp v58, v58, v58 row_ror:8 row_mask:0xf bank_mask:0xf bound_ctrl:1
	v_pk_fma_f32 v[64:65], v[52:53], v[166:167], v[64:65]
	v_pk_fma_f32 v[66:67], v[48:49], v[168:169], v[66:67]
	v_add_f32_dpp v58, v58, v58 row_ror:4 row_mask:0xf bank_mask:0xf bound_ctrl:1
	v_add_f32_dpp v60, v59, v59 row_ror:8 row_mask:0xf bank_mask:0xf bound_ctrl:1
	s_nop 0
	v_add_f32_dpp v58, v58, v58 row_ror:2 row_mask:0xf bank_mask:0xf bound_ctrl:1
	v_fma_f32 v61, v186, v189, v60
	s_nop 0
	v_add_f32_dpp v58, v58, v58 row_ror:1 row_mask:0xf bank_mask:0xf bound_ctrl:1
	v_pk_fma_f32 v[52:53], v[58:59], v[178:179], v[64:65] op_sel_hi:[0,1,1]
	v_pk_fma_f32 v[48:49], v[58:59], v[180:181], v[66:67] op_sel_hi:[0,1,1]
	v_fma_f32 v61, v58, v188, v61
	ds_read_b32 v54, v97 offset:28480
	ds_read_b64 v[56:57], v98 offset:28544
	ds_write_b32 v99, v61 offset:9216
	s_waitcnt lgkmcnt(9)
	v_pk_mul_f32 v[58:59], v[52:53], v[194:195] op_sel_hi:[0,1]
	ds_read_b128 v[170:173], v96 offset:28816
	ds_read_b128 v[174:177], v96 offset:29072
	v_pk_fma_f32 v[58:59], v[52:53], v[196:197], v[58:59] op_sel:[1,0,0]
	ds_read_b128 v[166:169], v96 offset:28560
	ds_read_b128 v[182:185], v96 offset:29584
	v_pk_fma_f32 v[58:59], v[48:49], v[198:199], v[58:59] op_sel_hi:[0,1,1]
	ds_read_b128 v[178:181], v96 offset:29328
	v_pk_fma_f32 v[58:59], v[48:49], v[200:201], v[58:59] op_sel:[1,0,0]
	v_pk_mul_f32 v[64:65], v[210:211], v[206:207] op_sel_hi:[0,1]
	v_pk_mul_f32 v[66:67], v[210:211], v[208:209] op_sel_hi:[0,1]
	v_add_f32_dpp v58, v58, v58 row_ror:8 row_mask:0xf bank_mask:0xf bound_ctrl:1
	v_pk_fma_f32 v[64:65], v[52:53], v[190:191], v[64:65]
	v_pk_fma_f32 v[66:67], v[48:49], v[192:193], v[66:67]
	v_add_f32_dpp v58, v58, v58 row_ror:4 row_mask:0xf bank_mask:0xf bound_ctrl:1
	v_add_f32_dpp v60, v59, v59 row_ror:8 row_mask:0xf bank_mask:0xf bound_ctrl:1
	s_nop 0
	v_add_f32_dpp v58, v58, v58 row_ror:2 row_mask:0xf bank_mask:0xf bound_ctrl:1
	v_fma_f32 v61, v210, v221, v60
	s_nop 0
	v_add_f32_dpp v58, v58, v58 row_ror:1 row_mask:0xf bank_mask:0xf bound_ctrl:1
	v_pk_fma_f32 v[52:53], v[58:59], v[202:203], v[64:65] op_sel_hi:[0,1,1]
	v_pk_fma_f32 v[48:49], v[58:59], v[204:205], v[66:67] op_sel_hi:[0,1,1]
	v_fma_f32 v61, v58, v220, v61
	ds_read_b32 v186, v97 offset:29840
	ds_read_b64 v[188:189], v98 offset:29904
	ds_write_b32 v99, v61 offset:9728
	s_waitcnt lgkmcnt(9)
	v_pk_mul_f32 v[58:59], v[52:53], v[32:33] op_sel_hi:[0,1]
	ds_read_b128 v[194:197], v96 offset:30176
	ds_read_b128 v[198:201], v96 offset:30432
	v_pk_fma_f32 v[58:59], v[52:53], v[34:35], v[58:59] op_sel:[1,0,0]
	ds_read_b128 v[190:193], v96 offset:29920
	ds_read_b128 v[206:209], v96 offset:30944
	v_pk_fma_f32 v[58:59], v[48:49], v[36:37], v[58:59] op_sel_hi:[0,1,1]
	ds_read_b128 v[202:205], v96 offset:30688
	v_pk_fma_f32 v[58:59], v[48:49], v[38:39], v[58:59] op_sel:[1,0,0]
	v_pk_mul_f32 v[64:65], v[54:55], v[44:45] op_sel_hi:[0,1]
	v_pk_mul_f32 v[66:67], v[54:55], v[46:47] op_sel_hi:[0,1]
	v_add_f32_dpp v58, v58, v58 row_ror:8 row_mask:0xf bank_mask:0xf bound_ctrl:1
	v_pk_fma_f32 v[64:65], v[52:53], v[28:29], v[64:65]
	v_pk_fma_f32 v[66:67], v[48:49], v[30:31], v[66:67]
	v_add_f32_dpp v58, v58, v58 row_ror:4 row_mask:0xf bank_mask:0xf bound_ctrl:1
	v_add_f32_dpp v60, v59, v59 row_ror:8 row_mask:0xf bank_mask:0xf bound_ctrl:1
	s_nop 0
	v_add_f32_dpp v58, v58, v58 row_ror:2 row_mask:0xf bank_mask:0xf bound_ctrl:1
	v_fma_f32 v61, v54, v57, v60
	s_nop 0
	v_add_f32_dpp v58, v58, v58 row_ror:1 row_mask:0xf bank_mask:0xf bound_ctrl:1
	v_pk_fma_f32 v[52:53], v[58:59], v[40:41], v[64:65] op_sel_hi:[0,1,1]
	v_pk_fma_f32 v[48:49], v[58:59], v[42:43], v[66:67] op_sel_hi:[0,1,1]
	v_fma_f32 v61, v58, v56, v61
	ds_read_b32 v210, v97 offset:31200
	ds_read_b64 v[220:221], v98 offset:31264
	ds_write_b32 v99, v61 offset:10240
	s_waitcnt lgkmcnt(9)
	v_pk_mul_f32 v[58:59], v[52:53], v[170:171] op_sel_hi:[0,1]
	ds_read_b128 v[32:35], v96 offset:31536
	ds_read_b128 v[36:39], v96 offset:31792
	v_pk_fma_f32 v[58:59], v[52:53], v[172:173], v[58:59] op_sel:[1,0,0]
	ds_read_b128 v[28:31], v96 offset:31280
	ds_read_b128 v[44:47], v96 offset:32304
	v_pk_fma_f32 v[58:59], v[48:49], v[174:175], v[58:59] op_sel_hi:[0,1,1]
	ds_read_b128 v[40:43], v96 offset:32048
	v_pk_fma_f32 v[58:59], v[48:49], v[176:177], v[58:59] op_sel:[1,0,0]
	v_pk_mul_f32 v[64:65], v[186:187], v[182:183] op_sel_hi:[0,1]
	v_pk_mul_f32 v[66:67], v[186:187], v[184:185] op_sel_hi:[0,1]
	v_add_f32_dpp v58, v58, v58 row_ror:8 row_mask:0xf bank_mask:0xf bound_ctrl:1
	v_pk_fma_f32 v[64:65], v[52:53], v[166:167], v[64:65]
	v_pk_fma_f32 v[66:67], v[48:49], v[168:169], v[66:67]
	v_add_f32_dpp v58, v58, v58 row_ror:4 row_mask:0xf bank_mask:0xf bound_ctrl:1
	v_add_f32_dpp v60, v59, v59 row_ror:8 row_mask:0xf bank_mask:0xf bound_ctrl:1
	s_nop 0
	v_add_f32_dpp v58, v58, v58 row_ror:2 row_mask:0xf bank_mask:0xf bound_ctrl:1
	v_fma_f32 v61, v186, v189, v60
	s_nop 0
	v_add_f32_dpp v58, v58, v58 row_ror:1 row_mask:0xf bank_mask:0xf bound_ctrl:1
	v_pk_fma_f32 v[52:53], v[58:59], v[178:179], v[64:65] op_sel_hi:[0,1,1]
	v_pk_fma_f32 v[48:49], v[58:59], v[180:181], v[66:67] op_sel_hi:[0,1,1]
	v_fma_f32 v61, v58, v188, v61
	ds_read_b32 v54, v97 offset:32560
	ds_read_b64 v[56:57], v98 offset:32624
	ds_write_b32 v99, v61 offset:10752
	s_waitcnt lgkmcnt(9)
	v_pk_mul_f32 v[58:59], v[52:53], v[194:195] op_sel_hi:[0,1]
	ds_read_b128 v[170:173], v96 offset:32896
	ds_read_b128 v[174:177], v96 offset:33152
	v_pk_fma_f32 v[58:59], v[52:53], v[196:197], v[58:59] op_sel:[1,0,0]
	ds_read_b128 v[166:169], v96 offset:32640
	ds_read_b128 v[182:185], v96 offset:33664
	v_pk_fma_f32 v[58:59], v[48:49], v[198:199], v[58:59] op_sel_hi:[0,1,1]
	ds_read_b128 v[178:181], v96 offset:33408
	v_pk_fma_f32 v[58:59], v[48:49], v[200:201], v[58:59] op_sel:[1,0,0]
	v_pk_mul_f32 v[64:65], v[210:211], v[206:207] op_sel_hi:[0,1]
	v_pk_mul_f32 v[66:67], v[210:211], v[208:209] op_sel_hi:[0,1]
	v_add_f32_dpp v58, v58, v58 row_ror:8 row_mask:0xf bank_mask:0xf bound_ctrl:1
	v_pk_fma_f32 v[64:65], v[52:53], v[190:191], v[64:65]
	v_pk_fma_f32 v[66:67], v[48:49], v[192:193], v[66:67]
	v_add_f32_dpp v58, v58, v58 row_ror:4 row_mask:0xf bank_mask:0xf bound_ctrl:1
	v_add_f32_dpp v60, v59, v59 row_ror:8 row_mask:0xf bank_mask:0xf bound_ctrl:1
	s_nop 0
	v_add_f32_dpp v58, v58, v58 row_ror:2 row_mask:0xf bank_mask:0xf bound_ctrl:1
	v_fma_f32 v61, v210, v221, v60
	s_nop 0
	v_add_f32_dpp v58, v58, v58 row_ror:1 row_mask:0xf bank_mask:0xf bound_ctrl:1
	v_pk_fma_f32 v[52:53], v[58:59], v[202:203], v[64:65] op_sel_hi:[0,1,1]
	v_pk_fma_f32 v[48:49], v[58:59], v[204:205], v[66:67] op_sel_hi:[0,1,1]
	v_fma_f32 v61, v58, v220, v61
	ds_read_b32 v186, v97 offset:33920
	ds_read_b64 v[188:189], v98 offset:33984
	ds_write_b32 v99, v61 offset:11264
	s_waitcnt lgkmcnt(9)
	v_pk_mul_f32 v[58:59], v[52:53], v[32:33] op_sel_hi:[0,1]
	ds_read_b128 v[194:197], v96 offset:34256
	ds_read_b128 v[198:201], v96 offset:34512
	v_pk_fma_f32 v[58:59], v[52:53], v[34:35], v[58:59] op_sel:[1,0,0]
	ds_read_b128 v[190:193], v96 offset:34000
	ds_read_b128 v[206:209], v96 offset:35024
	v_pk_fma_f32 v[58:59], v[48:49], v[36:37], v[58:59] op_sel_hi:[0,1,1]
	ds_read_b128 v[202:205], v96 offset:34768
	v_pk_fma_f32 v[58:59], v[48:49], v[38:39], v[58:59] op_sel:[1,0,0]
	v_pk_mul_f32 v[64:65], v[54:55], v[44:45] op_sel_hi:[0,1]
	v_pk_mul_f32 v[66:67], v[54:55], v[46:47] op_sel_hi:[0,1]
	v_add_f32_dpp v58, v58, v58 row_ror:8 row_mask:0xf bank_mask:0xf bound_ctrl:1
	v_pk_fma_f32 v[64:65], v[52:53], v[28:29], v[64:65]
	v_pk_fma_f32 v[66:67], v[48:49], v[30:31], v[66:67]
	v_add_f32_dpp v58, v58, v58 row_ror:4 row_mask:0xf bank_mask:0xf bound_ctrl:1
	v_add_f32_dpp v60, v59, v59 row_ror:8 row_mask:0xf bank_mask:0xf bound_ctrl:1
	s_nop 0
	v_add_f32_dpp v58, v58, v58 row_ror:2 row_mask:0xf bank_mask:0xf bound_ctrl:1
	v_fma_f32 v61, v54, v57, v60
	s_nop 0
	v_add_f32_dpp v58, v58, v58 row_ror:1 row_mask:0xf bank_mask:0xf bound_ctrl:1
	v_pk_fma_f32 v[52:53], v[58:59], v[40:41], v[64:65] op_sel_hi:[0,1,1]
	v_pk_fma_f32 v[48:49], v[58:59], v[42:43], v[66:67] op_sel_hi:[0,1,1]
	v_fma_f32 v61, v58, v56, v61
	ds_read_b32 v210, v97 offset:35280
	ds_read_b64 v[220:221], v98 offset:35344
	ds_write_b32 v99, v61 offset:11776
	s_waitcnt lgkmcnt(9)
	v_pk_mul_f32 v[58:59], v[52:53], v[170:171] op_sel_hi:[0,1]
	ds_read_b128 v[32:35], v96 offset:35616
	ds_read_b128 v[36:39], v96 offset:35872
	v_pk_fma_f32 v[58:59], v[52:53], v[172:173], v[58:59] op_sel:[1,0,0]
	ds_read_b128 v[28:31], v96 offset:35360
	ds_read_b128 v[44:47], v96 offset:36384
	v_pk_fma_f32 v[58:59], v[48:49], v[174:175], v[58:59] op_sel_hi:[0,1,1]
	ds_read_b128 v[40:43], v96 offset:36128
	v_pk_fma_f32 v[58:59], v[48:49], v[176:177], v[58:59] op_sel:[1,0,0]
	v_pk_mul_f32 v[64:65], v[186:187], v[182:183] op_sel_hi:[0,1]
	v_pk_mul_f32 v[66:67], v[186:187], v[184:185] op_sel_hi:[0,1]
	v_add_f32_dpp v58, v58, v58 row_ror:8 row_mask:0xf bank_mask:0xf bound_ctrl:1
	v_pk_fma_f32 v[64:65], v[52:53], v[166:167], v[64:65]
	v_pk_fma_f32 v[66:67], v[48:49], v[168:169], v[66:67]
	v_add_f32_dpp v58, v58, v58 row_ror:4 row_mask:0xf bank_mask:0xf bound_ctrl:1
	v_add_f32_dpp v60, v59, v59 row_ror:8 row_mask:0xf bank_mask:0xf bound_ctrl:1
	s_nop 0
	v_add_f32_dpp v58, v58, v58 row_ror:2 row_mask:0xf bank_mask:0xf bound_ctrl:1
	v_fma_f32 v61, v186, v189, v60
	s_nop 0
	v_add_f32_dpp v58, v58, v58 row_ror:1 row_mask:0xf bank_mask:0xf bound_ctrl:1
	v_pk_fma_f32 v[52:53], v[58:59], v[178:179], v[64:65] op_sel_hi:[0,1,1]
	v_pk_fma_f32 v[48:49], v[58:59], v[180:181], v[66:67] op_sel_hi:[0,1,1]
	v_fma_f32 v61, v58, v188, v61
	ds_read_b32 v54, v97 offset:36640
	ds_read_b64 v[56:57], v98 offset:36704
	ds_write_b32 v99, v61 offset:12288
	s_waitcnt lgkmcnt(9)
	v_pk_mul_f32 v[58:59], v[52:53], v[194:195] op_sel_hi:[0,1]
	ds_read_b128 v[170:173], v96 offset:36976
	ds_read_b128 v[174:177], v96 offset:37232
	v_pk_fma_f32 v[58:59], v[52:53], v[196:197], v[58:59] op_sel:[1,0,0]
	ds_read_b128 v[166:169], v96 offset:36720
	ds_read_b128 v[182:185], v96 offset:37744
	v_pk_fma_f32 v[58:59], v[48:49], v[198:199], v[58:59] op_sel_hi:[0,1,1]
	ds_read_b128 v[178:181], v96 offset:37488
	v_pk_fma_f32 v[58:59], v[48:49], v[200:201], v[58:59] op_sel:[1,0,0]
	v_pk_mul_f32 v[64:65], v[210:211], v[206:207] op_sel_hi:[0,1]
	v_pk_mul_f32 v[66:67], v[210:211], v[208:209] op_sel_hi:[0,1]
	v_add_f32_dpp v58, v58, v58 row_ror:8 row_mask:0xf bank_mask:0xf bound_ctrl:1
	v_pk_fma_f32 v[64:65], v[52:53], v[190:191], v[64:65]
	v_pk_fma_f32 v[66:67], v[48:49], v[192:193], v[66:67]
	v_add_f32_dpp v58, v58, v58 row_ror:4 row_mask:0xf bank_mask:0xf bound_ctrl:1
	v_add_f32_dpp v60, v59, v59 row_ror:8 row_mask:0xf bank_mask:0xf bound_ctrl:1
	s_nop 0
	v_add_f32_dpp v58, v58, v58 row_ror:2 row_mask:0xf bank_mask:0xf bound_ctrl:1
	v_fma_f32 v61, v210, v221, v60
	s_nop 0
	v_add_f32_dpp v58, v58, v58 row_ror:1 row_mask:0xf bank_mask:0xf bound_ctrl:1
	v_pk_fma_f32 v[52:53], v[58:59], v[202:203], v[64:65] op_sel_hi:[0,1,1]
	v_pk_fma_f32 v[48:49], v[58:59], v[204:205], v[66:67] op_sel_hi:[0,1,1]
	v_fma_f32 v61, v58, v220, v61
	ds_read_b32 v186, v97 offset:38000
	ds_read_b64 v[188:189], v98 offset:38064
	ds_write_b32 v99, v61 offset:12800
	s_waitcnt lgkmcnt(9)
	v_pk_mul_f32 v[58:59], v[52:53], v[32:33] op_sel_hi:[0,1]
	ds_read_b128 v[194:197], v96 offset:38336
	ds_read_b128 v[198:201], v96 offset:38592
	v_pk_fma_f32 v[58:59], v[52:53], v[34:35], v[58:59] op_sel:[1,0,0]
	ds_read_b128 v[190:193], v96 offset:38080
	ds_read_b128 v[206:209], v96 offset:39104
	v_pk_fma_f32 v[58:59], v[48:49], v[36:37], v[58:59] op_sel_hi:[0,1,1]
	ds_read_b128 v[202:205], v96 offset:38848
	v_pk_fma_f32 v[58:59], v[48:49], v[38:39], v[58:59] op_sel:[1,0,0]
	v_pk_mul_f32 v[64:65], v[54:55], v[44:45] op_sel_hi:[0,1]
	v_pk_mul_f32 v[66:67], v[54:55], v[46:47] op_sel_hi:[0,1]
	v_add_f32_dpp v58, v58, v58 row_ror:8 row_mask:0xf bank_mask:0xf bound_ctrl:1
	v_pk_fma_f32 v[64:65], v[52:53], v[28:29], v[64:65]
	v_pk_fma_f32 v[66:67], v[48:49], v[30:31], v[66:67]
	v_add_f32_dpp v58, v58, v58 row_ror:4 row_mask:0xf bank_mask:0xf bound_ctrl:1
	v_add_f32_dpp v60, v59, v59 row_ror:8 row_mask:0xf bank_mask:0xf bound_ctrl:1
	s_nop 0
	v_add_f32_dpp v58, v58, v58 row_ror:2 row_mask:0xf bank_mask:0xf bound_ctrl:1
	v_fma_f32 v61, v54, v57, v60
	s_nop 0
	v_add_f32_dpp v58, v58, v58 row_ror:1 row_mask:0xf bank_mask:0xf bound_ctrl:1
	v_pk_fma_f32 v[52:53], v[58:59], v[40:41], v[64:65] op_sel_hi:[0,1,1]
	v_pk_fma_f32 v[48:49], v[58:59], v[42:43], v[66:67] op_sel_hi:[0,1,1]
	v_fma_f32 v61, v58, v56, v61
	ds_read_b32 v210, v97 offset:39360
	ds_read_b64 v[220:221], v98 offset:39424
	ds_write_b32 v99, v61 offset:13312
	s_waitcnt lgkmcnt(9)
	v_pk_mul_f32 v[58:59], v[52:53], v[170:171] op_sel_hi:[0,1]
	ds_read_b128 v[32:35], v96 offset:39696
	ds_read_b128 v[36:39], v96 offset:39952
	v_pk_fma_f32 v[58:59], v[52:53], v[172:173], v[58:59] op_sel:[1,0,0]
	ds_read_b128 v[28:31], v96 offset:39440
	ds_read_b128 v[44:47], v96 offset:40464
	v_pk_fma_f32 v[58:59], v[48:49], v[174:175], v[58:59] op_sel_hi:[0,1,1]
	ds_read_b128 v[40:43], v96 offset:40208
	v_pk_fma_f32 v[58:59], v[48:49], v[176:177], v[58:59] op_sel:[1,0,0]
	v_pk_mul_f32 v[64:65], v[186:187], v[182:183] op_sel_hi:[0,1]
	v_pk_mul_f32 v[66:67], v[186:187], v[184:185] op_sel_hi:[0,1]
	v_add_f32_dpp v58, v58, v58 row_ror:8 row_mask:0xf bank_mask:0xf bound_ctrl:1
	v_pk_fma_f32 v[64:65], v[52:53], v[166:167], v[64:65]
	v_pk_fma_f32 v[66:67], v[48:49], v[168:169], v[66:67]
	v_add_f32_dpp v58, v58, v58 row_ror:4 row_mask:0xf bank_mask:0xf bound_ctrl:1
	v_add_f32_dpp v60, v59, v59 row_ror:8 row_mask:0xf bank_mask:0xf bound_ctrl:1
	s_nop 0
	v_add_f32_dpp v58, v58, v58 row_ror:2 row_mask:0xf bank_mask:0xf bound_ctrl:1
	v_fma_f32 v61, v186, v189, v60
	s_nop 0
	v_add_f32_dpp v58, v58, v58 row_ror:1 row_mask:0xf bank_mask:0xf bound_ctrl:1
	v_pk_fma_f32 v[52:53], v[58:59], v[178:179], v[64:65] op_sel_hi:[0,1,1]
	v_pk_fma_f32 v[48:49], v[58:59], v[180:181], v[66:67] op_sel_hi:[0,1,1]
	v_fma_f32 v61, v58, v188, v61
	ds_read_b32 v54, v97 offset:40720
	ds_read_b64 v[56:57], v98 offset:40784
	ds_write_b32 v99, v61 offset:13824
	s_waitcnt lgkmcnt(9)
	v_pk_mul_f32 v[58:59], v[52:53], v[194:195] op_sel_hi:[0,1]
	ds_read_b128 v[170:173], v96 offset:41056
	ds_read_b128 v[174:177], v96 offset:41312
	v_pk_fma_f32 v[58:59], v[52:53], v[196:197], v[58:59] op_sel:[1,0,0]
	ds_read_b128 v[166:169], v96 offset:40800
	ds_read_b128 v[182:185], v96 offset:41824
	v_pk_fma_f32 v[58:59], v[48:49], v[198:199], v[58:59] op_sel_hi:[0,1,1]
	ds_read_b128 v[178:181], v96 offset:41568
	v_pk_fma_f32 v[58:59], v[48:49], v[200:201], v[58:59] op_sel:[1,0,0]
	v_pk_mul_f32 v[64:65], v[210:211], v[206:207] op_sel_hi:[0,1]
	v_pk_mul_f32 v[66:67], v[210:211], v[208:209] op_sel_hi:[0,1]
	v_add_f32_dpp v58, v58, v58 row_ror:8 row_mask:0xf bank_mask:0xf bound_ctrl:1
	v_pk_fma_f32 v[64:65], v[52:53], v[190:191], v[64:65]
	v_pk_fma_f32 v[66:67], v[48:49], v[192:193], v[66:67]
	v_add_f32_dpp v58, v58, v58 row_ror:4 row_mask:0xf bank_mask:0xf bound_ctrl:1
	v_add_f32_dpp v60, v59, v59 row_ror:8 row_mask:0xf bank_mask:0xf bound_ctrl:1
	s_nop 0
	v_add_f32_dpp v58, v58, v58 row_ror:2 row_mask:0xf bank_mask:0xf bound_ctrl:1
	v_fma_f32 v61, v210, v221, v60
	s_nop 0
	v_add_f32_dpp v58, v58, v58 row_ror:1 row_mask:0xf bank_mask:0xf bound_ctrl:1
	v_pk_fma_f32 v[52:53], v[58:59], v[202:203], v[64:65] op_sel_hi:[0,1,1]
	v_pk_fma_f32 v[48:49], v[58:59], v[204:205], v[66:67] op_sel_hi:[0,1,1]
	v_fma_f32 v61, v58, v220, v61
	ds_read_b32 v186, v97 offset:42080
	ds_read_b64 v[188:189], v98 offset:42144
	ds_write_b32 v99, v61 offset:14336
	s_waitcnt lgkmcnt(9)
	v_pk_mul_f32 v[58:59], v[52:53], v[32:33] op_sel_hi:[0,1]
	ds_read_b128 v[194:197], v96 offset:42416
	ds_read_b128 v[198:201], v96 offset:42672
	v_pk_fma_f32 v[58:59], v[52:53], v[34:35], v[58:59] op_sel:[1,0,0]
	ds_read_b128 v[190:193], v96 offset:42160
	ds_read_b128 v[206:209], v96 offset:43184
	v_pk_fma_f32 v[58:59], v[48:49], v[36:37], v[58:59] op_sel_hi:[0,1,1]
	ds_read_b128 v[202:205], v96 offset:42928
	v_pk_fma_f32 v[58:59], v[48:49], v[38:39], v[58:59] op_sel:[1,0,0]
	v_pk_mul_f32 v[64:65], v[54:55], v[44:45] op_sel_hi:[0,1]
	v_pk_mul_f32 v[66:67], v[54:55], v[46:47] op_sel_hi:[0,1]
	v_add_f32_dpp v58, v58, v58 row_ror:8 row_mask:0xf bank_mask:0xf bound_ctrl:1
	v_pk_fma_f32 v[64:65], v[52:53], v[28:29], v[64:65]
	v_pk_fma_f32 v[66:67], v[48:49], v[30:31], v[66:67]
	v_add_f32_dpp v58, v58, v58 row_ror:4 row_mask:0xf bank_mask:0xf bound_ctrl:1
	v_add_f32_dpp v60, v59, v59 row_ror:8 row_mask:0xf bank_mask:0xf bound_ctrl:1
	s_nop 0
	v_add_f32_dpp v58, v58, v58 row_ror:2 row_mask:0xf bank_mask:0xf bound_ctrl:1
	v_fma_f32 v61, v54, v57, v60
	s_nop 0
	v_add_f32_dpp v58, v58, v58 row_ror:1 row_mask:0xf bank_mask:0xf bound_ctrl:1
	v_pk_fma_f32 v[52:53], v[58:59], v[40:41], v[64:65] op_sel_hi:[0,1,1]
	v_pk_fma_f32 v[48:49], v[58:59], v[42:43], v[66:67] op_sel_hi:[0,1,1]
	v_fma_f32 v61, v58, v56, v61
	ds_read_b32 v210, v97 offset:43440
	ds_read_b64 v[220:221], v98 offset:43504
	ds_write_b32 v99, v61 offset:14848
	s_waitcnt lgkmcnt(9)
	v_pk_mul_f32 v[58:59], v[52:53], v[170:171] op_sel_hi:[0,1]
	v_pk_fma_f32 v[58:59], v[52:53], v[172:173], v[58:59] op_sel:[1,0,0]
	v_pk_fma_f32 v[58:59], v[48:49], v[174:175], v[58:59] op_sel_hi:[0,1,1]
	v_pk_fma_f32 v[58:59], v[48:49], v[176:177], v[58:59] op_sel:[1,0,0]
	v_pk_mul_f32 v[64:65], v[186:187], v[182:183] op_sel_hi:[0,1]
	v_pk_mul_f32 v[66:67], v[186:187], v[184:185] op_sel_hi:[0,1]
	v_add_f32_dpp v58, v58, v58 row_ror:8 row_mask:0xf bank_mask:0xf bound_ctrl:1
	v_pk_fma_f32 v[64:65], v[52:53], v[166:167], v[64:65]
	v_pk_fma_f32 v[66:67], v[48:49], v[168:169], v[66:67]
	v_add_f32_dpp v58, v58, v58 row_ror:4 row_mask:0xf bank_mask:0xf bound_ctrl:1
	v_add_f32_dpp v60, v59, v59 row_ror:8 row_mask:0xf bank_mask:0xf bound_ctrl:1
	s_nop 0
	v_add_f32_dpp v58, v58, v58 row_ror:2 row_mask:0xf bank_mask:0xf bound_ctrl:1
	v_fma_f32 v61, v186, v189, v60
	s_nop 0
	v_add_f32_dpp v58, v58, v58 row_ror:1 row_mask:0xf bank_mask:0xf bound_ctrl:1
	v_pk_fma_f32 v[52:53], v[58:59], v[178:179], v[64:65] op_sel_hi:[0,1,1]
	v_pk_fma_f32 v[48:49], v[58:59], v[180:181], v[66:67] op_sel_hi:[0,1,1]
	v_fma_f32 v61, v58, v188, v61
	ds_write_b32 v99, v61 offset:15360
	s_waitcnt lgkmcnt(2)
	v_pk_mul_f32 v[58:59], v[52:53], v[194:195] op_sel_hi:[0,1]
	v_pk_fma_f32 v[58:59], v[52:53], v[196:197], v[58:59] op_sel:[1,0,0]
	v_pk_fma_f32 v[58:59], v[48:49], v[198:199], v[58:59] op_sel_hi:[0,1,1]
	v_pk_fma_f32 v[58:59], v[48:49], v[200:201], v[58:59] op_sel:[1,0,0]
	v_pk_mul_f32 v[64:65], v[210:211], v[206:207] op_sel_hi:[0,1]
	v_pk_mul_f32 v[66:67], v[210:211], v[208:209] op_sel_hi:[0,1]
	v_add_f32_dpp v58, v58, v58 row_ror:8 row_mask:0xf bank_mask:0xf bound_ctrl:1
	v_pk_fma_f32 v[64:65], v[52:53], v[190:191], v[64:65]
	v_pk_fma_f32 v[66:67], v[48:49], v[192:193], v[66:67]
	v_add_f32_dpp v58, v58, v58 row_ror:4 row_mask:0xf bank_mask:0xf bound_ctrl:1
	v_add_f32_dpp v60, v59, v59 row_ror:8 row_mask:0xf bank_mask:0xf bound_ctrl:1
	s_nop 0
	v_add_f32_dpp v58, v58, v58 row_ror:2 row_mask:0xf bank_mask:0xf bound_ctrl:1
	v_fma_f32 v61, v210, v221, v60
	s_nop 0
	v_add_f32_dpp v58, v58, v58 row_ror:1 row_mask:0xf bank_mask:0xf bound_ctrl:1
	v_pk_fma_f32 v[52:53], v[58:59], v[202:203], v[64:65] op_sel_hi:[0,1,1]
	v_pk_fma_f32 v[48:49], v[58:59], v[204:205], v[66:67] op_sel_hi:[0,1,1]
	v_fma_f32 v61, v58, v220, v61
	ds_write_b32 v99, v61 offset:15872
	s_setprio 0
	s_mov_b64 s[78:79], 0
